# weight f32->bf16 transposes of layers 1-3 (two thirds of them) deferred from phase 0 to the idle CU-mates of the scan workgroups in the previous layer's phase 4; plus gemm_in tail tiles at phase 4 sta
# baseline (speedup 1.0000x reference)
; __device__ __forceinline__ void phase_w(const Params p, char* smem) {
;     ...
;   for (int t = lbid(); t < L_ * PER_L; t += gridDim.x) {
;     int l = t / PER_L, r = t % PER_L;
;     if (r < 7392) {
;       transpose_tile<true>((const float*)p.in[I_WIN] + (size_t)l * D_ * NIN, NIN, (u16*)(ws + OFF_WIN) + (size_t)l * NINP * D_, D_,
;                      r / 231, r % 231, tile);
.LBB0_149:
	s_lshr_b32 s0, s73, 6
	s_cmp_eq_u32 s0, 4
	s_cbranch_scc0 .Lnot_mate
	v_readlane_b32 s0, v244, 43
	s_cmp_gt_u32 s0, 2
	s_cbranch_scc1 .LBB0_248
	s_add_i32 s0, s0, 1
	s_mul_i32 s20, s0, 0x2768
	s_add_i32 s101, s20, 6399
	s_add_i32 s20, s20, s73
	s_sub_i32 s20, s20, 0x100
	s_mov_b32 s100, 64
	s_branch .Ltramp_554

; __device__ __forceinline__ void phase_w(const Params p, char* smem) {
;     ...
;   for (int t = lbid(); t < L_ * PER_L; t += gridDim.x) {
;     int l = t / PER_L, r = t % PER_L;
.Lw_exit:
	s_cmp_eq_u32 s100, 64
	s_cbranch_scc1 .Lw_ret4
	s_cmp_eq_u32 s101, 0x9d9f
	s_cbranch_scc1 .LBB0_575
	s_add_i32 s20, s101, 6401
	s_add_i32 s101, s101, 0x2768
	s_add_i32 s20, s20, s73
	s_branch .LBB0_554
